# conv epilogue head: norm-bias row loads issued with the row-sum loads (one memory round trip instead of two)
# baseline (speedup 1.0000x reference)
.LBB0_326:
	v_mov_b32_e32 v159, v225
	s_lshl_b32 s52, s44, 7
	v_ashrrev_i32_e32 v0, 7, v159
	v_and_b32_e32 v34, 0x7f, v159
	s_movk_i32 s2, 0x1600
	v_or_b32_e32 v54, s52, v34
	v_cmp_gt_i32_e32 vcc, 3, v0
	v_mul_lo_u32 v55, v0, s2
	v_mov_b32_e32 v34, s75
	v_mov_b32_e32 v35, s73
	s_sub_i32 s43, s42, 32
	v_cndmask_b32_e32 v0, 0, v55, vcc
	v_cndmask_b32_e32 v35, v34, v35, vcc
	v_mov_b32_e32 v34, s74
	v_mov_b32_e32 v36, s72
	s_lshr_b32 s2, s43, 3
	v_add_u32_e32 v0, v0, v54
	v_cndmask_b32_e32 v34, v34, v36, vcc
	s_add_i32 s2, s2, 1
	v_lshl_add_u64 v[36:37], v[0:1], 2, v[34:35]
	s_cmp_gt_i32 s42, 31
	global_load_dword v161, v[36:37], off
	v_add_u32_e32 v0, 0xb00, v55
	v_mov_b32_e32 v36, 0xb00
	s_cselect_b32 s2, s2, 0
	s_lshl_b32 s3, s42, 8
	v_and_b32_e32 v199, 15, v159
	v_cndmask_b32_e32 v0, v36, v0, vcc
	s_add_i32 s3, s3, s76
	v_add_u32_e32 v0, v0, v54
	v_or_b32_e32 v208, s3, v199
	v_lshl_add_u64 v[34:35], v[0:1], 2, v[34:35]
	v_ashrrev_i32_e32 v209, 31, v208
	global_load_dword v163, v[34:35], off
	v_lshl_add_u64 v[34:35], s[60:61], 0, v[208:209]
	v_lshl_add_u64 v[34:35], v[34:35], 4, s[56:57]
	global_load_dwordx4 v[54:57], v[34:35], off
	global_load_dwordx4 v[218:221], v[34:35], off offset:256
	global_load_dwordx4 v[228:231], v[34:35], off offset:512
	global_load_dwordx4 v[232:235], v[34:35], off offset:768
	global_load_dwordx4 v[240:243], v[34:35], off offset:2048
	global_load_dwordx4 v[244:247], v[34:35], off offset:2304
	global_load_dwordx4 v[248:251], v[34:35], off offset:2560
	global_load_dwordx4 v[34:37], v[34:35], off offset:2816
	v_lshrrev_b32_e32 v0, 1, v159
	v_and_or_b32 v206, v0, 24, s77
	s_mul_i32 s3, s18, 3
	s_add_u32 s46, s3, s2
	s_mul_hi_i32 s2, s18, 3
	s_addc_u32 s2, s2, 0
	s_mulk_i32 s2, 0x5800
	s_mul_hi_u32 s45, s46, 0x5800
	s_add_i32 s45, s45, s2
	s_lshl_b32 s2, s44, 8
	s_mulk_i32 s46, 0x5800
	s_ashr_i32 s3, s2, 31
	s_add_u32 s4, s87, s46
	s_addc_u32 s45, s88, s45
	s_lshl_b64 s[2:3], s[2:3], 2
	s_add_u32 s44, s4, s2
	s_addc_u32 s45, s45, s3
	v_lshlrev_b32_e32 v106, 2, v206
	v_cmp_lt_i32_e32 vcc, 14, v199
	s_mov_b64 s[46:47], 0
	global_load_dwordx4 v[210:213], v106, s[44:45] offset:16
	global_load_dwordx4 v[138:141], v106, s[44:45]
	global_load_dwordx4 v[214:217], v106, s[44:45] offset:528
	s_nop 0
	global_load_dwordx4 v[106:109], v106, s[44:45] offset:512
	s_waitcnt vmcnt(11)
	v_mov_b32_e32 v252, v55
	v_mov_b32_e32 v253, v56
	v_mov_b32_e32 v55, v57
	v_pk_add_f32 v[252:253], v[252:253], v[54:55]
	s_nop 0
	v_add_f32_e32 v252, v252, v253
	v_fmamk_f32 v252, v252, 0x3a800000, v223
	v_rsq_f32_e32 v0, v252
	s_waitcnt vmcnt(10)
	v_mov_b32_e32 v252, v219
	v_mov_b32_e32 v253, v220
	v_mov_b32_e32 v219, v221
	v_pk_add_f32 v[252:253], v[252:253], v[218:219]
	s_nop 0
	v_add_f32_e32 v252, v252, v253
	v_fmamk_f32 v252, v252, 0x3a800000, v223
	v_rsq_f32_e32 v202, v252
	s_waitcnt vmcnt(9)
	v_mov_b32_e32 v252, v229
	v_mov_b32_e32 v253, v230
	v_mov_b32_e32 v229, v231
	v_pk_add_f32 v[252:253], v[252:253], v[228:229]
	s_nop 0
	v_add_f32_e32 v252, v252, v253
	v_fmamk_f32 v252, v252, 0x3a800000, v223
	v_rsq_f32_e32 v204, v252
	s_waitcnt vmcnt(8)
	v_mov_b32_e32 v252, v233
	v_mov_b32_e32 v253, v234
	v_mov_b32_e32 v233, v235
	v_pk_add_f32 v[252:253], v[252:253], v[232:233]
	s_nop 0
	v_add_f32_e32 v252, v252, v253
	v_fmamk_f32 v252, v252, 0x3a800000, v223
	v_rsq_f32_e32 v158, v252
	s_waitcnt vmcnt(7)
	v_mov_b32_e32 v252, v241
	v_mov_b32_e32 v253, v242
	v_mov_b32_e32 v241, v243
	v_pk_add_f32 v[252:253], v[252:253], v[240:241]
	s_nop 0
	v_add_f32_e32 v252, v252, v253
	v_fmamk_f32 v252, v252, 0x3a800000, v223
	v_rsq_f32_e32 v160, v252
	s_waitcnt vmcnt(6)
	v_mov_b32_e32 v252, v245
	v_mov_b32_e32 v253, v246
	v_mov_b32_e32 v245, v247
	v_pk_add_f32 v[252:253], v[252:253], v[244:245]
	s_nop 0
	v_add_f32_e32 v252, v252, v253
	v_fmamk_f32 v252, v252, 0x3a800000, v223
	v_rsq_f32_e32 v198, v252
	s_waitcnt vmcnt(5)
	v_mov_b32_e32 v252, v249
	v_mov_b32_e32 v253, v250
	v_mov_b32_e32 v249, v251
	v_pk_add_f32 v[252:253], v[252:253], v[248:249]
	s_nop 0
	v_add_f32_e32 v252, v252, v253
	v_fmamk_f32 v252, v252, 0x3a800000, v223
	v_rsq_f32_e32 v200, v252
	s_waitcnt vmcnt(4)
	v_mov_b32_e32 v252, v35
	v_mov_b32_e32 v253, v36
	v_mov_b32_e32 v35, v37
	v_pk_add_f32 v[252:253], v[252:253], v[34:35]
	s_nop 0
	v_add_f32_e32 v252, v252, v253
	v_fmamk_f32 v252, v252, 0x3a800000, v223
	v_rsq_f32_e32 v162, v252
	s_and_saveexec_b64 s[44:45], vcc
	s_xor_b64 s[44:45], exec, s[44:45]
	s_mov_b64 s[46:47], exec
	s_or_saveexec_b64 s[44:45], s[44:45]
	s_waitcnt vmcnt(2)
	v_pk_fma_f32 v[144:145], v[144:145], v[158:159], v[140:141] op_sel_hi:[1,0,1]
	v_pk_fma_f32 v[142:143], v[142:143], v[158:159], v[138:139] op_sel_hi:[1,0,1]
	v_pk_fma_f32 v[152:153], v[88:89], v[0:1], v[140:141] op_sel_hi:[1,0,1]
	v_mov_b64_e32 v[156:157], v[144:145]
	v_pk_fma_f32 v[150:151], v[86:87], v[0:1], v[138:139] op_sel_hi:[1,0,1]
	v_mov_b32_e32 v164, s92
	v_cmp_eq_u32_e32 vcc, 0, v199
	v_mov_b64_e32 v[154:155], v[142:143]
	s_xor_b64 exec, exec, s[44:45]
	s_andn2_b64 s[46:47], s[46:47], exec
	s_and_b64 s[48:49], vcc, exec
	v_mov_b64_e32 v[156:157], v[152:153]
	v_mov_b32_e32 v164, s89
	s_or_b64 s[46:47], s[46:47], s[48:49]
	v_mov_b64_e32 v[154:155], v[150:151]
	s_or_b64 exec, exec, s[44:45]
	v_mov_b64_e32 v[54:55], v[210:211]
	v_mov_b64_e32 v[56:57], v[212:213]
	v_pk_fma_f32 v[88:89], v[52:53], v[0:1], v[56:57] op_sel_hi:[1,0,1]
	v_pk_fma_f32 v[86:87], v[50:51], v[0:1], v[54:55] op_sel_hi:[1,0,1]
	v_pk_fma_f32 v[84:85], v[84:85], v[158:159], v[56:57] op_sel_hi:[1,0,1]
	v_pk_fma_f32 v[82:83], v[82:83], v[158:159], v[54:55] op_sel_hi:[1,0,1]
	v_pk_fma_f32 v[132:133], v[132:133], v[160:161], v[140:141] op_sel_hi:[1,0,1]
	v_pk_fma_f32 v[130:131], v[130:131], v[160:161], v[138:139] op_sel_hi:[1,0,1]
	v_pk_fma_f32 v[52:53], v[136:137], v[160:161], v[56:57] op_sel_hi:[1,0,1]
	v_pk_fma_f32 v[50:51], v[134:135], v[160:161], v[54:55] op_sel_hi:[1,0,1]
	v_pk_fma_f32 v[120:121], v[120:121], v[162:163], v[140:141] op_sel_hi:[1,0,1]
	v_pk_fma_f32 v[118:119], v[118:119], v[162:163], v[138:139] op_sel_hi:[1,0,1]
	v_pk_fma_f32 v[48:49], v[48:49], v[162:163], v[56:57] op_sel_hi:[1,0,1]
	v_pk_fma_f32 v[46:47], v[46:47], v[162:163], v[54:55] op_sel_hi:[1,0,1]
	s_waitcnt vmcnt(0)
	v_mov_b64_e32 v[34:35], v[214:215]
	v_mov_b64_e32 v[36:37], v[216:217]
	v_pk_fma_f32 v[148:149], v[80:81], v[0:1], v[108:109] op_sel_hi:[1,0,1]
	v_pk_fma_f32 v[146:147], v[78:79], v[0:1], v[106:107] op_sel_hi:[1,0,1]
	v_pk_fma_f32 v[80:81], v[76:77], v[0:1], v[36:37] op_sel_hi:[1,0,1]
	v_pk_fma_f32 v[78:79], v[74:75], v[0:1], v[34:35] op_sel_hi:[1,0,1]
	v_pk_fma_f32 v[136:137], v[44:45], v[158:159], v[108:109] op_sel_hi:[1,0,1]
	v_pk_fma_f32 v[134:135], v[42:43], v[158:159], v[106:107] op_sel_hi:[1,0,1]
	v_pk_fma_f32 v[76:77], v[40:41], v[158:159], v[36:37] op_sel_hi:[1,0,1]
	v_pk_fma_f32 v[74:75], v[38:39], v[158:159], v[34:35] op_sel_hi:[1,0,1]
	v_pk_fma_f32 v[116:117], v[116:117], v[160:161], v[108:109] op_sel_hi:[1,0,1]
	v_pk_fma_f32 v[114:115], v[114:115], v[160:161], v[106:107] op_sel_hi:[1,0,1]
	v_pk_fma_f32 v[44:45], v[128:129], v[160:161], v[36:37] op_sel_hi:[1,0,1]
	v_pk_fma_f32 v[42:43], v[126:127], v[160:161], v[34:35] op_sel_hi:[1,0,1]
	v_pk_fma_f32 v[112:113], v[112:113], v[162:163], v[108:109] op_sel_hi:[1,0,1]
	v_pk_fma_f32 v[110:111], v[110:111], v[162:163], v[106:107] op_sel_hi:[1,0,1]
	v_pk_fma_f32 v[40:41], v[124:125], v[162:163], v[36:37] op_sel_hi:[1,0,1]
	v_pk_fma_f32 v[38:39], v[122:123], v[162:163], v[34:35] op_sel_hi:[1,0,1]
	s_and_saveexec_b64 s[44:45], s[46:47]
	s_cbranch_execz .LBB0_367
	v_mov_b64_e32 v[124:125], v[84:85]
	v_lshl_add_u32 v0, v206, 2, v164
	v_cmp_gt_i32_e32 vcc, 15, v199
	s_mov_b64 s[48:49], -1
	v_mov_b32_e32 v126, 0x410
	v_mov_b64_e32 v[122:123], v[82:83]
	ds_write_b128 v0, v[154:157]
	s_and_saveexec_b64 s[46:47], vcc
	s_cbranch_execz .LBB0_335
	v_cmp_eq_u32_e32 vcc, 0, v199
	s_mov_b64 s[48:49], 0
	v_mov_b32_e32 v126, 0x410
	s_and_saveexec_b64 s[50:51], vcc
	s_mov_b64 s[48:49], exec
	v_mov_b32_e32 v126, 16
	s_or_b64 exec, exec, s[50:51]
	v_mov_b64_e32 v[124:125], v[88:89]
	s_orn2_b64 s[48:49], s[48:49], exec
	v_mov_b64_e32 v[122:123], v[86:87]
